# RMW scan pass: cross-term tile stores staged through LDS into coalesced dwordx4 stores
# speedup vs baseline: 1.0310x; 1.0128x over previous
; #define LAS __attribute__((address_space(3)))
; #define MFMA32(a, b, c) __builtin_amdgcn_mfma_f32_32x32x16_bf16((a), (b), (c), 0, 0, 0)
; template <bool XW, int PASS, bool RMW> ...
;     ...
;         const LAS bf16_t* sp = Sb + pbuf * SBE + r * 264 + 8 * h;
; #pragma unroll
;         for (int sb = 0; sb < 8; ++sb) {
;           bf16x8 a0[2], a1[2];
; #pragma unroll
;           for (int k = 0; k < 2; ++k) { a0[k] = *(const LAS bf16x8*)(sp + 16 * (2 * sb + k)); a1[k] = *(const LAS bf16x8*)(sp + 32 * 264 + 16 * (2 * sb + k)); }
; #pragma unroll
;           for (int k = 0; k < 2; ++k) { yc0 = MFMA32(a0[k], qf[2 * sb + k], yc0); yc1 = MFMA32(a1[k], qf[2 * sb + k], yc1); }
;         }
;     ...
;       for (int i = 0; i < 16; ++i) { st0[i] *= cd; st1[i] *= cd; }
.LBB0_102:
	s_add_i32 s8, s2, 1
	v_mov_b32_e32 v32, s8
	s_add_i32 s2, s2, 2
	v_sub_u32_e64 v169, s5, v32 clamp
	v_mov_b32_e32 v32, s2
	s_mul_i32 s2, s0, 0x8400
	v_add_u32_e32 v204, s2, v217
	v_sub_u32_e64 v203, s5, v32 clamp
	ds_read_b128 v[232:235], v204
	ds_read_b128 v[236:239], v204 offset:16896
	ds_read_b128 v[240:243], v204 offset:32
	ds_read_b128 v[244:247], v204 offset:16928
	ds_read_b128 v[248:251], v204 offset:64
	s_waitcnt vmcnt(37)
	s_waitcnt lgkmcnt(4)
	v_mfma_f32_32x32x16_bf16 v[48:63], v[232:235], v[120:123], 0
	ds_read_b128 v[232:235], v204 offset:16960
	v_lshlrev_b32_e32 v206, 18, v169
	s_waitcnt vmcnt(17)
	v_lshlrev_b32_e32 v205, 16, v188
	s_and_b32 s2, s1, 0x4000
	v_mul_f32_e64 v16, v182, v16
	v_mul_f32_e64 v17, v183, v17
	v_pk_mul_f32 v[0:1], v[182:183], v[0:1]
	s_addk_i32 s1, 0x4000
	s_xor_b32 s0, s0, 1
	s_waitcnt lgkmcnt(4)
	v_mfma_f32_32x32x16_bf16 v[32:47], v[236:239], v[120:123], 0
	ds_read_b128 v[236:239], v204 offset:96
	ds_read_b128 v[120:123], v204 offset:16992
	s_waitcnt lgkmcnt(5)
	v_mfma_f32_32x32x16_bf16 v[48:63], v[240:243], v[124:127], v[48:63]
	ds_read_b128 v[240:243], v204 offset:128
	s_waitcnt lgkmcnt(5)
	v_mfma_f32_32x32x16_bf16 v[32:47], v[244:247], v[124:127], v[32:47]
	ds_read_b128 v[244:247], v204 offset:17024
	ds_read_b128 v[124:127], v204 offset:160
	s_waitcnt lgkmcnt(6)
	v_mfma_f32_32x32x16_bf16 v[48:63], v[248:251], v[112:115], v[48:63]
	ds_read_b128 v[248:251], v204 offset:17056
	s_waitcnt lgkmcnt(6)
	v_mfma_f32_32x32x16_bf16 v[32:47], v[232:235], v[112:115], v[32:47]
	ds_read_b128 v[232:235], v204 offset:192
	ds_read_b128 v[112:115], v204 offset:17088
	s_waitcnt lgkmcnt(7)
	v_mfma_f32_32x32x16_bf16 v[48:63], v[236:239], v[116:119], v[48:63]
	ds_read_b128 v[236:239], v204 offset:224
	s_waitcnt lgkmcnt(7)
	v_mfma_f32_32x32x16_bf16 v[32:47], v[120:123], v[116:119], v[32:47]
	ds_read_b128 v[120:123], v204 offset:17120
	s_waitcnt lgkmcnt(7)
	v_mfma_f32_32x32x16_bf16 v[48:63], v[240:243], v[104:107], v[48:63]
	ds_read_b128 v[240:243], v204 offset:256
	s_waitcnt lgkmcnt(7)
	v_mfma_f32_32x32x16_bf16 v[32:47], v[244:247], v[104:107], v[32:47]
	ds_read_b128 v[244:247], v204 offset:17152
	s_waitcnt lgkmcnt(7)
	v_mfma_f32_32x32x16_bf16 v[48:63], v[124:127], v[108:111], v[48:63]
	ds_read_b128 v[124:127], v204 offset:288
	s_waitcnt lgkmcnt(7)
	v_mfma_f32_32x32x16_bf16 v[32:47], v[248:251], v[108:111], v[32:47]
	ds_read_b128 v[248:251], v204 offset:17184
	s_waitcnt lgkmcnt(7)
	v_mfma_f32_32x32x16_bf16 v[48:63], v[232:235], v[96:99], v[48:63]
	ds_read_b128 v[232:235], v204 offset:320
	s_waitcnt lgkmcnt(7)
	v_mfma_f32_32x32x16_bf16 v[32:47], v[112:115], v[96:99], v[32:47]
	ds_read_b128 v[112:115], v204 offset:17216
	s_waitcnt lgkmcnt(7)
	v_mfma_f32_32x32x16_bf16 v[48:63], v[236:239], v[100:103], v[48:63]
	ds_read_b128 v[236:239], v204 offset:352
	s_waitcnt lgkmcnt(7)
	v_mfma_f32_32x32x16_bf16 v[32:47], v[120:123], v[100:103], v[32:47]
	ds_read_b128 v[120:123], v204 offset:17248
	s_waitcnt lgkmcnt(7)
	v_mfma_f32_32x32x16_bf16 v[48:63], v[240:243], v[88:91], v[48:63]
	ds_read_b128 v[240:243], v204 offset:384
	s_waitcnt lgkmcnt(7)
	v_mfma_f32_32x32x16_bf16 v[32:47], v[244:247], v[88:91], v[32:47]
	ds_read_b128 v[244:247], v204 offset:17280
	s_waitcnt lgkmcnt(7)
	v_mfma_f32_32x32x16_bf16 v[48:63], v[124:127], v[92:95], v[48:63]
	ds_read_b128 v[124:127], v204 offset:416
	s_waitcnt lgkmcnt(7)
	v_mfma_f32_32x32x16_bf16 v[32:47], v[248:251], v[92:95], v[32:47]
	ds_read_b128 v[248:251], v204 offset:17312
	s_waitcnt lgkmcnt(7)
	v_mfma_f32_32x32x16_bf16 v[48:63], v[232:235], v[80:83], v[48:63]
	ds_read_b128 v[232:235], v204 offset:448
	s_waitcnt lgkmcnt(7)
	v_mfma_f32_32x32x16_bf16 v[32:47], v[112:115], v[80:83], v[32:47]
	ds_read_b128 v[112:115], v204 offset:17344
	s_waitcnt lgkmcnt(7)
	v_mfma_f32_32x32x16_bf16 v[48:63], v[236:239], v[84:87], v[48:63]
	ds_read_b128 v[236:239], v204 offset:480
	s_waitcnt lgkmcnt(7)
	v_mfma_f32_32x32x16_bf16 v[32:47], v[120:123], v[84:87], v[32:47]
	ds_read_b128 v[120:123], v204 offset:17376
	s_waitcnt lgkmcnt(7)
	v_mfma_f32_32x32x16_bf16 v[48:63], v[240:243], v[72:75], v[48:63]
	s_waitcnt lgkmcnt(6)
	v_mfma_f32_32x32x16_bf16 v[32:47], v[244:247], v[72:75], v[32:47]
	s_waitcnt lgkmcnt(5)
	v_mfma_f32_32x32x16_bf16 v[48:63], v[124:127], v[76:79], v[48:63]
	s_waitcnt lgkmcnt(4)
	v_mfma_f32_32x32x16_bf16 v[32:47], v[248:251], v[76:79], v[32:47]
	v_add_u32_e32 v204, 64, v231
	s_waitcnt lgkmcnt(3)
	v_mfma_f32_32x32x16_bf16 v[48:63], v[232:235], v[64:67], v[48:63]
	s_waitcnt lgkmcnt(2)
	v_mfma_f32_32x32x16_bf16 v[32:47], v[112:115], v[64:67], v[32:47]
	s_waitcnt lgkmcnt(1)
	v_mfma_f32_32x32x16_bf16 v[48:63], v[236:239], v[68:71], v[48:63]
	s_waitcnt lgkmcnt(0)
; DI unsigned cvt_pk_bf16(float lo, float hi) { unsigned r; asm volatile("v_cvt_pk_bf16_f32 %0, %1, %2" : "=v"(r) : "v"(lo), "v"(hi)); return r; }
; DI float bf_lo(unsigned w) { return __uint_as_float(w << 16); }
; DI float bf_hi(unsigned w) { return __uint_as_float(w & 0xffff0000u); }
; template <bool XW, int PASS, bool RMW> ...
;     ...
; #pragma unroll
;         for (int s = 0; s < 16; ++s) qf[s] = ldg16(qr, qoff0 + (unsigned)cn * 262144u + 1024u * s);
;         const float qe = cc > 0 ? qd : 0.f;
; #pragma unroll
;         for (int gq = 0; gq < 4; ++gq) {
;           u32x2 a; a.x = cvt_pk_bf16(bf_lo(ovn[gq].x) + qe * yc0[4 * gq], bf_hi(ovn[gq].x) + qe * yc0[4 * gq + 1]); a.y = cvt_pk_bf16(bf_lo(ovn[gq].y) + qe * yc0[4 * gq + 2], bf_hi(ovn[gq].y) + qe * yc0[4 * gq + 3]);
;           *(u32x2*)((char*)y + (yb + 16u * gq)) = a;
;           u32x2 c2; c2.x = cvt_pk_bf16(bf_lo(ovn[4 + gq].x) + qe * yc1[4 * gq], bf_hi(ovn[4 + gq].x) + qe * yc1[4 * gq + 1]); c2.y = cvt_pk_bf16(bf_lo(ovn[4 + gq].y) + qe * yc1[4 * gq + 2], bf_hi(ovn[4 + gq].y) + qe * yc1[4 * gq + 3]);
;           *(u32x2*)((char*)y + (yb + 64u + 16u * gq)) = c2;
;         }
	v_mfma_f32_32x32x16_bf16 v[32:47], v[120:123], v[68:71], v[32:47]
	v_add_u32_e32 v68, v206, v226
	v_or_b32_e32 v64, 0x400, v68
	global_load_dwordx4 v[120:123], v68, s[92:93]
	global_load_dwordx4 v[124:127], v64, s[92:93]
	v_or_b32_e32 v64, 0x800, v68
	global_load_dwordx4 v[112:115], v64, s[92:93]
	v_or_b32_e32 v64, 0xc00, v68
	global_load_dwordx4 v[116:119], v64, s[92:93]
	v_or_b32_e32 v64, 0x1000, v68
	global_load_dwordx4 v[104:107], v64, s[92:93]
	v_or_b32_e32 v64, 0x1400, v68
	global_load_dwordx4 v[108:111], v64, s[92:93]
	v_or_b32_e32 v64, 0x1800, v68
	global_load_dwordx4 v[96:99], v64, s[92:93]
	v_or_b32_e32 v64, 0x1c00, v68
	global_load_dwordx4 v[100:103], v64, s[92:93]
	v_or_b32_e32 v64, 0x2000, v68
	global_load_dwordx4 v[88:91], v64, s[92:93]
	v_or_b32_e32 v64, 0x2400, v68
	global_load_dwordx4 v[92:95], v64, s[92:93]
	v_or_b32_e32 v64, 0x2800, v68
	global_load_dwordx4 v[80:83], v64, s[92:93]
	v_or_b32_e32 v64, 0x2c00, v68
	global_load_dwordx4 v[84:87], v64, s[92:93]
	v_or_b32_e32 v64, 0x3000, v68
	global_load_dwordx4 v[72:75], v64, s[92:93]
	v_or_b32_e32 v64, 0x3400, v68
	v_fmac_f32_e32 v205, v230, v48
	v_and_b32_e32 v48, 0xffff0000, v188
	global_load_dwordx4 v[76:79], v64, s[92:93]
	v_or_b32_e32 v64, 0x3800, v68
	v_or_b32_e32 v68, 0x3c00, v68
	v_fmac_f32_e32 v48, v230, v49
	v_lshlrev_b32_e32 v49, 16, v189
	global_load_dwordx4 v[64:67], v64, s[92:93]
	v_fmac_f32_e32 v49, v230, v50
	global_load_dwordx4 v[68:71], v68, s[92:93]
	v_cvt_pk_bf16_f32 v48, v205, v48
	v_and_b32_e32 v50, 0xffff0000, v189
	v_fmac_f32_e32 v50, v230, v51
	v_cvt_pk_bf16_f32 v49, v49, v50
	v_mbcnt_lo_u32_b32 v211, -1, 0
	v_mbcnt_hi_u32_b32 v211, -1, v211
	v_readlane_b32 s100, v255, 12
	v_and_b32_e32 v207, 31, v211
	v_lshrrev_b32_e32 v208, 5, v211
	v_lshrrev_b32_e32 v209, 3, v211
	v_and_b32_e32 v210, 7, v211
	v_mov_b32_e32 v211, s100
	v_mul_u32_u24_e32 v211, 0x44, v211
	v_add_u32_e32 v211, 0x1a000, v211
	v_mul_u32_u24_e32 v252, 0x88, v207
	v_lshl_add_u32 v252, v208, 3, v252
	v_add_u32_e32 v252, v211, v252
	v_mul_u32_u24_e32 v253, 0x88, v209
	v_lshl_add_u32 v253, v210, 4, v253
	v_add_u32_e32 v253, v211, v253
	v_sub_u32_e32 v248, v209, v207
	v_lshlrev_b32_e32 v248, 12, v248
	v_lshl_add_u32 v248, v210, 4, v248
	v_lshlrev_b32_e32 v208, 3, v208
	v_sub_u32_e32 v248, v248, v208
	v_add_u32_e32 v248, v231, v248
	v_add_u32_e32 v249, 0x8000, v248
	v_add_u32_e32 v250, 0x10000, v248
	v_add_u32_e32 v251, 0x18000, v248
	ds_write_b64 v252, v[48:49]
	s_waitcnt vmcnt(29)
	v_lshlrev_b32_e32 v48, 16, v186
	v_fmac_f32_e32 v48, v230, v32
	v_and_b32_e32 v32, 0xffff0000, v186
	v_fmac_f32_e32 v32, v230, v33
	v_lshlrev_b32_e32 v33, 16, v187
	v_fmac_f32_e32 v33, v230, v34
	v_and_b32_e32 v34, 0xffff0000, v187
	v_cvt_pk_bf16_f32 v32, v48, v32
	v_fmac_f32_e32 v34, v230, v35
	v_cvt_pk_bf16_f32 v33, v33, v34
	ds_write_b64 v252, v[32:33] offset:64
	v_lshlrev_b32_e32 v32, 16, v184
	v_and_b32_e32 v33, 0xffff0000, v184
	v_fmac_f32_e32 v32, v230, v52
	v_fmac_f32_e32 v33, v230, v53
	v_cvt_pk_bf16_f32 v32, v32, v33
	v_lshlrev_b32_e32 v33, 16, v185
	v_and_b32_e32 v34, 0xffff0000, v185
	v_fmac_f32_e32 v33, v230, v54
	v_fmac_f32_e32 v34, v230, v55
	v_cvt_pk_bf16_f32 v33, v33, v34
	v_add_u32_e32 v34, 16, v231
	ds_write_b64 v252, v[32:33] offset:16
	s_waitcnt vmcnt(28)
	v_lshlrev_b32_e32 v32, 16, v180
	v_and_b32_e32 v33, 0xffff0000, v180
	v_fmac_f32_e32 v32, v230, v36
	v_fmac_f32_e32 v33, v230, v37
	v_cvt_pk_bf16_f32 v32, v32, v33
	v_lshlrev_b32_e32 v33, 16, v181
	v_and_b32_e32 v34, 0xffff0000, v181
	v_fmac_f32_e32 v33, v230, v38
	v_fmac_f32_e32 v34, v230, v39
	v_cvt_pk_bf16_f32 v33, v33, v34
	v_add_u32_e32 v34, 0x50, v231
	ds_write_b64 v252, v[32:33] offset:80
	v_lshlrev_b32_e32 v32, 16, v178
	v_and_b32_e32 v33, 0xffff0000, v178
	v_fmac_f32_e32 v32, v230, v56
	v_fmac_f32_e32 v33, v230, v57
	v_cvt_pk_bf16_f32 v32, v32, v33
	v_lshlrev_b32_e32 v33, 16, v179
	v_and_b32_e32 v34, 0xffff0000, v179
	v_fmac_f32_e32 v33, v230, v58
	v_fmac_f32_e32 v34, v230, v59
	v_cvt_pk_bf16_f32 v33, v33, v34
	v_add_u32_e32 v34, 32, v231
	ds_write_b64 v252, v[32:33] offset:32
	s_waitcnt vmcnt(27)
	v_lshlrev_b32_e32 v32, 16, v174
	v_and_b32_e32 v33, 0xffff0000, v174
	v_fmac_f32_e32 v32, v230, v40
	v_fmac_f32_e32 v33, v230, v41
	v_cvt_pk_bf16_f32 v32, v32, v33
	v_lshlrev_b32_e32 v33, 16, v175
	v_and_b32_e32 v34, 0xffff0000, v175
	v_fmac_f32_e32 v33, v230, v42
	v_fmac_f32_e32 v34, v230, v43
	v_cvt_pk_bf16_f32 v33, v33, v34
	v_add_u32_e32 v34, 0x60, v231
	ds_write_b64 v252, v[32:33] offset:96
	v_lshlrev_b32_e32 v32, 16, v172
	v_and_b32_e32 v33, 0xffff0000, v172
	v_fmac_f32_e32 v32, v230, v60
	v_fmac_f32_e32 v33, v230, v61
	v_cvt_pk_bf16_f32 v32, v32, v33
	v_lshlrev_b32_e32 v33, 16, v173
	v_and_b32_e32 v34, 0xffff0000, v173
	v_fmac_f32_e32 v33, v230, v62
	v_fmac_f32_e32 v34, v230, v63
	v_cvt_pk_bf16_f32 v33, v33, v34
	v_add_u32_e32 v34, 48, v231
	ds_write_b64 v252, v[32:33] offset:48
	s_waitcnt vmcnt(26)
	v_lshlrev_b32_e32 v32, 16, v170
	v_and_b32_e32 v33, 0xffff0000, v170
	v_fmac_f32_e32 v32, v230, v44
	v_fmac_f32_e32 v33, v230, v45
	v_cvt_pk_bf16_f32 v32, v32, v33
	v_lshlrev_b32_e32 v33, 16, v171
	v_and_b32_e32 v34, 0xffff0000, v171
	v_fmac_f32_e32 v33, v230, v46
	v_fmac_f32_e32 v34, v230, v47
	v_cvt_pk_bf16_f32 v33, v33, v34
	v_add_u32_e32 v34, 0x70, v231
	ds_write_b64 v252, v[32:33] offset:112
	s_waitcnt lgkmcnt(0)
	ds_read_b128 v[232:235], v253
	ds_read_b128 v[236:239], v253 offset:1088
	ds_read_b128 v[240:243], v253 offset:2176
	ds_read_b128 v[244:247], v253 offset:3264
	s_waitcnt lgkmcnt(0)
; #define LAS __attribute__((address_space(3)))
; DI unsigned cvt_pk_bf16(float lo, float hi) { unsigned r; asm volatile("v_cvt_pk_bf16_f32 %0, %1, %2" : "=v"(r) : "v"(lo), "v"(hi)); return r; }
; DI float bf_lo(unsigned w) { return __uint_as_float(w << 16); }
; DI float bf_hi(unsigned w) { return __uint_as_float(w & 0xffff0000u); }
; template <bool XW, int PASS, bool RMW> ...
;     ...
;         for (int gq = 0; gq < 4; ++gq) {
;           u32x2 a; a.x = cvt_pk_bf16(bf_lo(ovn[gq].x) + qe * yc0[4 * gq], bf_hi(ovn[gq].x) + qe * yc0[4 * gq + 1]); a.y = cvt_pk_bf16(bf_lo(ovn[gq].y) + qe * yc0[4 * gq + 2], bf_hi(ovn[gq].y) + qe * yc0[4 * gq + 3]);
;           *(u32x2*)((char*)y + (yb + 16u * gq)) = a;
;           u32x2 c2; c2.x = cvt_pk_bf16(bf_lo(ovn[4 + gq].x) + qe * yc1[4 * gq], bf_hi(ovn[4 + gq].x) + qe * yc1[4 * gq + 1]); c2.y = cvt_pk_bf16(bf_lo(ovn[4 + gq].y) + qe * yc1[4 * gq + 2], bf_hi(ovn[4 + gq].y) + qe * yc1[4 * gq + 3]);
;           *(u32x2*)((char*)y + (yb + 64u + 16u * gq)) = c2;
;         }
;         if constexpr (PASS == 1 && RMW) {
;           const unsigned ybn = yoff0 + (unsigned)cn * 524288u;
; #pragma unroll
;           for (int gq = 0; gq < 8; ++gq) ovn[gq] = *(const u32x2*)((const char*)y + (ybn + 64u * (gq >> 2) + 16u * (gq & 3)));
;         }
;       }
; #pragma unroll
;       for (int i = 0; i < 16; ++i) { st0[i] *= cd; st1[i] *= cd; }
; #pragma unroll
;       for (int sb = 0; sb < 2; ++sb) {
;         bf16x8 a0[4], a1[4];
; #pragma unroll
;         for (int k = 0; k < 4; ++k) { a0[k] = *(const LAS bf16x8*)(vimg + (cc & 1) * 16384 + (4 * sb + k) * 1024 + lane * 16); a1[k] = *(const LAS bf16x8*)(vimg + (cc & 1) * 16384 + 8192 + (4 * sb + k) * 1024 + lane * 16); }
; #pragma unroll
;         for (int k = 0; k < 4; ++k) { st0 = MFMA32(a0[k], kb0[4 * sb + k], st0); st1 = MFMA32(a1[k], kb0[4 * sb + k], st1); }
;         asm volatile("" : "+v"(st0), "+v"(st1) :: "memory");
; #pragma unroll
;         for (int k = 0; k < 4; ++k) kb0[4 * sb + k] = ldg16(kT, kboff0 + (unsigned)cn * 262144u + 1024u * (4 * sb + k));
;       }
; #pragma unroll
;       for (int t = 0; t < 2; ++t) {
;         const int sv = 2 * dq + t;
;         *(LAS bf16x8*)(vimg + ((cc + 1) & 1) * 16384 + et * 8192 + sv * 1024 + lane * 16) = scale_tab(vr[t], kdec + 16 * sv + 8 * h);
;         vr[t] = ldg16(vT, vaoff0 + (unsigned)cnn * 524288u + 1024u * sv);
;       }
	global_store_dwordx4 v248, v[232:235], s[18:19]
	global_store_dwordx4 v249, v[236:239], s[18:19]
	global_store_dwordx4 v250, v[240:243], s[18:19]
	global_store_dwordx4 v251, v[244:247], s[18:19]
	s_nop 1
	v_lshl_add_u32 v32, v169, 19, v227
	v_or_b32_e32 v33, 16, v32
	global_load_dwordx2 v[188:189], v32, s[18:19]
	global_load_dwordx2 v[184:185], v33, s[18:19]
	v_or_b32_e32 v33, 32, v32
	global_load_dwordx2 v[178:179], v33, s[18:19]
	v_or_b32_e32 v33, 48, v32
	global_load_dwordx2 v[172:173], v33, s[18:19]
	v_or_b32_e32 v33, 64, v32
	global_load_dwordx2 v[186:187], v33, s[18:19]
	v_or_b32_e32 v33, 0x50, v32
	v_mov_b32_e32 v169, v168
	global_load_dwordx2 v[180:181], v33, s[18:19]
	v_or_b32_e32 v33, 0x60, v32
	v_or_b32_e32 v32, 0x70, v32
	v_pk_mul_f32 v[30:31], v[168:169], v[30:31]
	v_pk_mul_f32 v[28:29], v[168:169], v[28:29]
	v_pk_mul_f32 v[26:27], v[168:169], v[26:27]
	v_pk_mul_f32 v[24:25], v[168:169], v[24:25]
	v_pk_mul_f32 v[22:23], v[168:169], v[22:23]
	v_pk_mul_f32 v[20:21], v[168:169], v[20:21]
	v_pk_mul_f32 v[18:19], v[168:169], v[18:19]
	v_pk_mul_f32 v[14:15], v[168:169], v[14:15]
	v_pk_mul_f32 v[12:13], v[168:169], v[12:13]
	v_pk_mul_f32 v[10:11], v[168:169], v[10:11]
	v_pk_mul_f32 v[8:9], v[168:169], v[8:9]
	v_pk_mul_f32 v[6:7], v[168:169], v[6:7]
	v_pk_mul_f32 v[4:5], v[168:169], v[4:5]
	v_pk_mul_f32 v[2:3], v[168:169], v[2:3]
	v_add_u32_e32 v169, s2, v218
	global_load_dwordx2 v[174:175], v33, s[18:19]
	global_load_dwordx2 v[170:171], v32, s[18:19]
	ds_read_b128 v[32:35], v169
	ds_read_b128 v[36:39], v169 offset:8192
	ds_read_b128 v[40:43], v169 offset:1024
	ds_read_b128 v[44:47], v169 offset:9216
	ds_read_b128 v[48:51], v169 offset:2048
	ds_read_b128 v[52:55], v169 offset:10240
	ds_read_b128 v[56:59], v169 offset:3072
	ds_read_b128 v[60:63], v169 offset:11264
	s_waitcnt vmcnt(37) lgkmcnt(7)
	v_mfma_f32_32x32x16_bf16 v[16:31], v[32:35], v[128:131], v[16:31]
	v_add_u32_e32 v204, v206, v223
	v_or_b32_e32 v32, 0x400, v204
	s_and_b32 s2, s1, 0x4000
	v_add_u32_e32 v231, 0xfff80000, v231
	s_cmp_eq_u32 s4, s8
	s_waitcnt lgkmcnt(6)
	v_mfma_f32_32x32x16_bf16 v[0:15], v[36:39], v[128:131], v[0:15]
	s_waitcnt vmcnt(36) lgkmcnt(5)
	v_mfma_f32_32x32x16_bf16 v[16:31], v[40:43], v[132:135], v[16:31]
	s_waitcnt lgkmcnt(4)
	v_mfma_f32_32x32x16_bf16 v[0:15], v[44:47], v[132:135], v[0:15]
	s_waitcnt vmcnt(35) lgkmcnt(3)
	v_mfma_f32_32x32x16_bf16 v[16:31], v[48:51], v[136:139], v[16:31]
	s_waitcnt lgkmcnt(2)
	v_mfma_f32_32x32x16_bf16 v[0:15], v[52:55], v[136:139], v[0:15]
	s_waitcnt vmcnt(34) lgkmcnt(1)
	v_mfma_f32_32x32x16_bf16 v[16:31], v[56:59], v[140:143], v[16:31]
	s_waitcnt lgkmcnt(0)
	v_mfma_f32_32x32x16_bf16 v[0:15], v[60:63], v[140:143], v[0:15]
	global_load_dwordx4 v[128:131], v204, s[14:15]
	global_load_dwordx4 v[132:135], v32, s[14:15]
	v_or_b32_e32 v32, 0x800, v204
	global_load_dwordx4 v[136:139], v32, s[14:15]
	v_or_b32_e32 v32, 0xc00, v204
	global_load_dwordx4 v[140:143], v32, s[14:15]
	ds_read_b128 v[32:35], v169 offset:4096
	ds_read_b128 v[36:39], v169 offset:12288
	ds_read_b128 v[40:43], v169 offset:5120
	ds_read_b128 v[44:47], v169 offset:13312
	ds_read_b128 v[48:51], v169 offset:6144
	ds_read_b128 v[52:55], v169 offset:14336
	ds_read_b128 v[56:59], v169 offset:7168
	ds_read_b128 v[60:63], v169 offset:15360
	s_waitcnt vmcnt(37) lgkmcnt(7)
	v_mfma_f32_32x32x16_bf16 v[16:31], v[32:35], v[144:147], v[16:31]
	v_or_b32_e32 v32, 0x1000, v204
	s_waitcnt lgkmcnt(6)
	v_mfma_f32_32x32x16_bf16 v[0:15], v[36:39], v[144:147], v[0:15]
	s_waitcnt vmcnt(36) lgkmcnt(5)
	v_mfma_f32_32x32x16_bf16 v[16:31], v[40:43], v[148:151], v[16:31]
	s_waitcnt vmcnt(33)
	v_lshlrev_b32_e32 v42, 16, v160
	v_add_u32_e32 v40, s2, v198
	v_lshl_add_u32 v41, v203, 19, v224
	s_mul_i32 s2, s0, 0x8400
	s_waitcnt lgkmcnt(4)
	v_mfma_f32_32x32x16_bf16 v[0:15], v[44:47], v[148:151], v[0:15]
	s_waitcnt lgkmcnt(3)
	v_mfma_f32_32x32x16_bf16 v[16:31], v[48:51], v[152:155], v[16:31]
	s_waitcnt lgkmcnt(2)
	v_mfma_f32_32x32x16_bf16 v[0:15], v[52:55], v[152:155], v[0:15]
	s_waitcnt lgkmcnt(1)
	v_mfma_f32_32x32x16_bf16 v[16:31], v[56:59], v[156:159], v[16:31]
	s_waitcnt lgkmcnt(0)
	v_mfma_f32_32x32x16_bf16 v[0:15], v[60:63], v[156:159], v[0:15]
	global_load_dwordx4 v[144:147], v32, s[14:15]
	v_or_b32_e32 v32, 0x1400, v204
	global_load_dwordx4 v[148:151], v32, s[14:15]
	v_or_b32_e32 v32, 0x1800, v204
	global_load_dwordx4 v[152:155], v32, s[14:15]
	v_or_b32_e32 v32, 0x1c00, v204
	global_load_dwordx4 v[156:159], v32, s[14:15]
	ds_read_b128 v[32:35], v228
	ds_read_b128 v[36:39], v228 offset:16
	s_waitcnt lgkmcnt(1)
; #define LAS __attribute__((address_space(3)))
; DI unsigned cvt_pk_bf16(float lo, float hi) { unsigned r; asm volatile("v_cvt_pk_bf16_f32 %0, %1, %2" : "=v"(r) : "v"(lo), "v"(hi)); return r; }
; DI float bf_lo(unsigned w) { return __uint_as_float(w << 16); }
; DI float bf_hi(unsigned w) { return __uint_as_float(w & 0xffff0000u); }
; DI bf16x8 scale_tab(bf16x8 v, const LAS float* d) {
;   const f32x4 d0 = *(const LAS f32x4*)d, d1 = *(const LAS f32x4*)(d + 4);
;   const u32x4 wv = __builtin_bit_cast(u32x4, v); u32x4 o;
;   o.x = cvt_pk_bf16(bf_lo(wv.x) * d0[0], bf_hi(wv.x) * d0[1]); o.y = cvt_pk_bf16(bf_lo(wv.y) * d0[2], bf_hi(wv.y) * d0[3]);
;   o.z = cvt_pk_bf16(bf_lo(wv.z) * d1[0], bf_hi(wv.z) * d1[1]); o.w = cvt_pk_bf16(bf_lo(wv.w) * d1[2], bf_hi(wv.w) * d1[3]);
;   return __builtin_bit_cast(bf16x8, o);
; }
; template <bool XW, int PASS, bool RMW> ...
;     ...
;       for (int t = 0; t < 2; ++t) {
;         const int sv = 2 * dq + t;
;         *(LAS bf16x8*)(vimg + ((cc + 1) & 1) * 16384 + et * 8192 + sv * 1024 + lane * 16) = scale_tab(vr[t], kdec + 16 * sv + 8 * h);
;         vr[t] = ldg16(vT, vaoff0 + (unsigned)cnn * 524288u + 1024u * sv);
;       }
;       LAS bf16_t* sw = Sb + (pbuf ^ 1) * SBE + (4 * h) * 264 + 32 * w + r;
; #pragma unroll
;       for (int i = 0; i < 16; ++i) {
;         const int eo = ((i & 3) + 8 * (i >> 2)) * 264;
;         const unsigned pkw = cvt_pk_bf16(st0[i], st1[i]);
;         sw[eo] = (bf16_t)(pkw & 0xffffu);
;         sw[eo + 32 * 264] = (bf16_t)(pkw >> 16);
;       }
;       lds_barrier();
;       pbuf ^= 1;
	v_mul_f32_e32 v32, v32, v42
	v_and_b32_e32 v42, 0xffff0000, v160
	v_mul_f32_e32 v33, v33, v42
	v_cvt_pk_bf16_f32 v32, v32, v33
	v_lshlrev_b32_e32 v33, 16, v161
	v_mul_f32_e32 v33, v34, v33
	v_and_b32_e32 v34, 0xffff0000, v161
	v_mul_f32_e32 v34, v35, v34
	v_cvt_pk_bf16_f32 v33, v33, v34
	v_lshlrev_b32_e32 v34, 16, v162
	v_and_b32_e32 v35, 0xffff0000, v162
	s_waitcnt lgkmcnt(0)
	v_mul_f32_e32 v34, v36, v34
	v_mul_f32_e32 v35, v37, v35
	v_cvt_pk_bf16_f32 v34, v34, v35
	v_lshlrev_b32_e32 v35, 16, v163
	v_and_b32_e32 v36, 0xffff0000, v163
	v_mul_f32_e32 v35, v38, v35
	v_mul_f32_e32 v36, v39, v36
	v_cvt_pk_bf16_f32 v35, v35, v36
	v_add_u32_e32 v36, s3, v40
	ds_write_b128 v36, v[32:35]
	v_or_b32_e32 v32, s3, v41
	global_load_dwordx4 v[160:163], v32, s[16:17]
	ds_read_b128 v[32:35], v229
	ds_read_b128 v[36:39], v229 offset:16
	s_waitcnt vmcnt(37)
	v_lshlrev_b32_e32 v42, 16, v164
	s_waitcnt lgkmcnt(1)
	v_mul_f32_e32 v32, v32, v42
	v_and_b32_e32 v42, 0xffff0000, v164
	v_mul_f32_e32 v33, v33, v42
	v_cvt_pk_bf16_f32 v32, v32, v33
	v_lshlrev_b32_e32 v33, 16, v165
	v_mul_f32_e32 v33, v34, v33
	v_and_b32_e32 v34, 0xffff0000, v165
	v_mul_f32_e32 v34, v35, v34
	v_cvt_pk_bf16_f32 v33, v33, v34
	v_lshlrev_b32_e32 v34, 16, v166
	v_and_b32_e32 v35, 0xffff0000, v166
	s_waitcnt lgkmcnt(0)
	v_mul_f32_e32 v34, v36, v34
	v_mul_f32_e32 v35, v37, v35
	v_cvt_pk_bf16_f32 v34, v34, v35
	v_lshlrev_b32_e32 v35, 16, v167
	v_and_b32_e32 v36, 0xffff0000, v167
	v_mul_f32_e32 v35, v38, v35
	v_mul_f32_e32 v36, v39, v36
	v_cvt_pk_bf16_f32 v35, v35, v36
	v_add_u32_e32 v36, s33, v40
	ds_write_b128 v36, v[32:35]
	v_or_b32_e32 v32, s33, v41
	global_load_dwordx4 v[164:167], v32, s[16:17]
	v_add_u32_e32 v32, s2, v199
	v_mbcnt_lo_u32_b32 v251, -1, 0
	v_mbcnt_hi_u32_b32 v251, -1, v251
	v_and_b32_e32 v251, 1, v251
	v_sub_u32_e32 v250, 0, v251
	v_and_b32_e32 v248, 0x06060606, v250
	v_xor_b32_e32 v248, 0x05040100, v248
	v_and_b32_e32 v251, 0x107e, v250
	v_add_u32_e32 v249, v32, v251
	v_cvt_pk_bf16_f32 v232, v16, v20
	v_cvt_pk_bf16_f32 v233, v17, v21
	v_cvt_pk_bf16_f32 v234, v18, v22
	v_cvt_pk_bf16_f32 v235, v19, v23
	v_cvt_pk_bf16_f32 v236, v24, v28
	v_cvt_pk_bf16_f32 v237, v25, v29
	v_cvt_pk_bf16_f32 v238, v26, v30
	v_cvt_pk_bf16_f32 v239, v27, v31
	v_mov_b32_dpp v240, v232 quad_perm:[1,0,3,2] row_mask:0xf bank_mask:0xf
	v_mov_b32_dpp v241, v233 quad_perm:[1,0,3,2] row_mask:0xf bank_mask:0xf
	v_mov_b32_dpp v242, v234 quad_perm:[1,0,3,2] row_mask:0xf bank_mask:0xf
	v_mov_b32_dpp v243, v235 quad_perm:[1,0,3,2] row_mask:0xf bank_mask:0xf
	v_mov_b32_dpp v244, v236 quad_perm:[1,0,3,2] row_mask:0xf bank_mask:0xf
	v_mov_b32_dpp v245, v237 quad_perm:[1,0,3,2] row_mask:0xf bank_mask:0xf
	v_mov_b32_dpp v246, v238 quad_perm:[1,0,3,2] row_mask:0xf bank_mask:0xf
	v_mov_b32_dpp v247, v239 quad_perm:[1,0,3,2] row_mask:0xf bank_mask:0xf
	v_perm_b32 v240, v240, v232, v248
	v_perm_b32 v241, v241, v233, v248
	v_perm_b32 v242, v242, v234, v248
	v_perm_b32 v243, v243, v235, v248
	v_perm_b32 v244, v244, v236, v248
	v_perm_b32 v245, v245, v237, v248
	v_perm_b32 v246, v246, v238, v248
	v_perm_b32 v247, v247, v239, v248
	ds_write_b32 v249, v240 offset:0
	ds_write_b32 v249, v241 offset:528
	ds_write_b32 v249, v242 offset:1056
	ds_write_b32 v249, v243 offset:1584
	ds_write_b32 v249, v244 offset:8448
	ds_write_b32 v249, v245 offset:8976
	ds_write_b32 v249, v246 offset:9504
	ds_write_b32 v249, v247 offset:10032
	v_cvt_pk_bf16_f32 v232, v0, v4
	v_cvt_pk_bf16_f32 v233, v1, v5
	v_cvt_pk_bf16_f32 v234, v2, v6
	v_cvt_pk_bf16_f32 v235, v3, v7
	v_cvt_pk_bf16_f32 v236, v8, v12
	v_cvt_pk_bf16_f32 v237, v9, v13
	v_cvt_pk_bf16_f32 v238, v10, v14
	v_cvt_pk_bf16_f32 v239, v11, v15
	v_mov_b32_dpp v240, v232 quad_perm:[1,0,3,2] row_mask:0xf bank_mask:0xf
	v_mov_b32_dpp v241, v233 quad_perm:[1,0,3,2] row_mask:0xf bank_mask:0xf
	v_mov_b32_dpp v242, v234 quad_perm:[1,0,3,2] row_mask:0xf bank_mask:0xf
	v_mov_b32_dpp v243, v235 quad_perm:[1,0,3,2] row_mask:0xf bank_mask:0xf
	v_mov_b32_dpp v244, v236 quad_perm:[1,0,3,2] row_mask:0xf bank_mask:0xf
	v_mov_b32_dpp v245, v237 quad_perm:[1,0,3,2] row_mask:0xf bank_mask:0xf
	v_mov_b32_dpp v246, v238 quad_perm:[1,0,3,2] row_mask:0xf bank_mask:0xf
	v_mov_b32_dpp v247, v239 quad_perm:[1,0,3,2] row_mask:0xf bank_mask:0xf
	v_perm_b32 v240, v240, v232, v248
	v_perm_b32 v241, v241, v233, v248
	v_perm_b32 v242, v242, v234, v248
	v_perm_b32 v243, v243, v235, v248
	v_perm_b32 v244, v244, v236, v248
	v_perm_b32 v245, v245, v237, v248
	v_perm_b32 v246, v246, v238, v248
	v_perm_b32 v247, v247, v239, v248
	ds_write_b32 v249, v240 offset:16896
	ds_write_b32 v249, v241 offset:17424
	ds_write_b32 v249, v242 offset:17952
	ds_write_b32 v249, v243 offset:18480
	ds_write_b32 v249, v244 offset:25344
	ds_write_b32 v249, v245 offset:25872
	ds_write_b32 v249, v246 offset:26400
	ds_write_b32 v249, v247 offset:26928
	s_waitcnt lgkmcnt(0)
	s_barrier
	s_mov_b32 s2, s8
	s_cbranch_scc0 .LBB0_102
